# combined + GLU MIX store coalescing + a mid-file trampoline for the phase-end branch (code grew past the simm16 branch range)
# baseline (speedup 1.0000x reference)
; __global__ void __launch_bounds__(512, 2) fwd_kernel(Args args) {
;     ...
;     for (int ph = lo; ph < hi; ++ph) {
;       const int cls_ = ph < 3 ? ph : 3 + ((ph - 3) & 7);
;       const int nrep_ = ((((DUPM) >> cls_) & 1u) && !(cls_ == 8 && ph >= 11) && cls_ != 10) ? 2 : 1;
;       for (int rep_ = 0; rep_ < nrep_; ++rep_) {
;         if ((ph > lo || rep_) && cls_ != 5) { if (hi < 0) cg::this_grid().sync(); else xcd_barrier(xbar); }
.LBB0_411:
	s_and_b64 vcc, exec, s[42:43]
	s_waitcnt lgkmcnt(0)
	s_barrier
	s_branch .LBB0_417
.Ltramp_8:
	s_branch .LBB0_8
.LBB0_417:
	s_mov_b64 s[6:7], 0
